# NSA tile loop edge: far block carries its own copy of the loop latch and one combined far-tile test (loop-edge edit)
# baseline (speedup 1.0000x reference)
; #define LAS __attribute__((address_space(3)))
; __device__ __forceinline__ float ex2(float x) { return __builtin_amdgcn_exp2f(x); }
; __device__ __forceinline__ void nsa_unit(const Params& p, LAS unsigned char* lds, int b, int hkv, int i, int tid, int lane, int wave) {
;     ...
;         for (int it = 0; it < nt; ++it) {
;             const int j = msb64(crem); crem &= ~(1ull << j);
;             const int ahead = nt - 1 - it;
;             RING_WAIT(ahead);
;             if (it + 3 < nt) { const int ji = msb64(irem); irem &= ~(1ull << ji); rg.issue(Kb + (size_t)ji * 64 * ZW, ZW, Vb + (size_t)ji * 64 * ZW, ZW, (it + 3) & 3); }
;                 if ((wm >> j) & 1ull) {
;                     const LAS unsigned char* stg = lds + (it & 3) * STG_BYTES;
;                     const int dj = i - j;
;                     const bool lsel = (lm >> j) & 1ull;
;                     const int db = 64 * dj + tq - 4 * hi;
; #pragma unroll
;                     for (int hf = 0; hf < 2; ++hf) {
;                         f32x16 s; unsigned pw[8];
;                         if (dj <= 2) {
;                             qk_half(stg, qf, col, hi, hf, s, -mref);
;                             const LAS float* l2p = (const LAS float*)(lds + LUT2_OFF) + head * 260 + db + 5;
; #pragma unroll
;                             for (int r = 0; r < 16; ++r) { const float x = s[r] + l2p[63 - KKOF(hf, r)]; s[r] = (lsel && KKOF(hf, r) <= db) ? ex2(x) : 0.f; }
; #pragma unroll
;                             for (int r = 0; r < 8; ++r) pw[r] = pk2(s[2 * r], s[2 * r + 1]);
;                         } else if (dj == 8) {
;                             qk_half_c(stg, qf, col, hi, hf, s, cfar);
; #pragma unroll
;                             for (int r = 0; r < 16; ++r) { const int d_ = db - KKOF(hf, r); s[r] = (lsel && d_ < dmax) ? ex2(s[r]) : 0.f; }
; #pragma unroll
;                             for (int r = 0; r < 8; ++r) pw[r] = pk2(s[2 * r], s[2 * r + 1]);
;                         } else {
;                             qk_half_c(stg, qf, col, hi, hf, s, cfar);
; #pragma unroll
;                             for (int r = 0; r < 8; ++r) { const unsigned w_ = pk2(ex2(s[2 * r]), ex2(s[2 * r + 1])); pw[r] = lsel ? w_ : 0u; }
;                         }
;                         pv_half_tr(stg + 8192, pw, tra, hf, o0, o1, os, ones);
;                     }
.LBB0_563:
	s_flbit_i32_b64 s0, s[34:35]
	s_xor_b32 s4, s0, 63
	s_lshl_b64 s[2:3], 1, s4
	s_and_b64 s[10:11], s[2:3], s[48:49]
	s_cmp_eq_u64 s[10:11], 0
	s_cbranch_scc1 .Lskip_tile
	s_and_b32 s0, s79, 0xc000
	s_add_i32 s0, s0, 0
	v_and_b32_e32 v253, s3, v214
	v_and_b32_e32 v252, s2, v215
	v_cmp_eq_u64_e64 s[22:23], 0, v[252:253]
	s_sub_i32 s4, s67, s4
	s_cmp_gt_i32 s4, 2
	s_cselect_b64 s[12:13], -1, 0
	s_cmp_lg_u32 s4, 8
	v_lshl_add_u32 v2, s4, 6, v212
	s_cselect_b64 s[10:11], -1, 0
	s_mov_b64 s[14:15], -1
	s_min_u32 s5, s4, 31
	s_lshl_b32 s5, 1, s5
	s_and_b32 s5, s5, 0x107
	s_cbranch_scc1 .Lnotfar
	v_add3_u32 v248, s0, v208, v209
	v_add3_u32 v249, s0, v208, v210
	ds_read_b64_tr_b16 v[236:237], v248 offset:8192
	ds_read_b64_tr_b16 v[238:239], v248 offset:9216
	ds_read_b64_tr_b16 v[240:241], v249 offset:8192
	ds_read_b64_tr_b16 v[242:243], v249 offset:9216
	ds_read_b64_tr_b16 v[244:245], v248 offset:10240
	ds_read_b64_tr_b16 v[246:247], v248 offset:11264
	s_waitcnt lgkmcnt(9)
	v_mfma_f32_32x32x16_bf16 v[100:115], v[4:7], v[148:151], v[68:83]
	ds_read_b128 v[4:7], v125 offset:4096
	s_waitcnt lgkmcnt(9)
	v_mfma_f32_32x32x16_bf16 v[100:115], v[8:11], v[152:155], v[100:115]
	ds_read_b128 v[8:11], v126 offset:4096
	s_waitcnt lgkmcnt(9)
	v_mfma_f32_32x32x16_bf16 v[100:115], v[12:15], v[156:159], v[100:115]
	ds_read_b128 v[12:15], v127 offset:4096
	s_waitcnt lgkmcnt(9)
	v_mfma_f32_32x32x16_bf16 v[100:115], v[116:119], v[160:163], v[100:115]
	ds_read_b128 v[116:119], v128 offset:4096
	v_mov_b32_e32 v252, s88
	v_mov_b32_e32 v253, s88
	v_mov_b32_e32 v254, s88
	v_mov_b32_e32 v255, s88
	s_waitcnt lgkmcnt(3)
	v_mfma_f32_32x32x16_bf16 v[220:235], v[4:7], v[148:151], v[68:83]
	s_waitcnt lgkmcnt(2)
	v_mfma_f32_32x32x16_bf16 v[220:235], v[8:11], v[152:155], v[220:235]
	s_nop 2
	v_exp_f32_e32 v100, v100
	v_exp_f32_e32 v101, v101
	v_exp_f32_e32 v102, v102
	v_exp_f32_e32 v103, v103
	s_waitcnt lgkmcnt(1)
	v_mfma_f32_32x32x16_bf16 v[220:235], v[12:15], v[156:159], v[220:235]
	v_exp_f32_e32 v104, v104
	v_exp_f32_e32 v105, v105
	v_exp_f32_e32 v106, v106
	v_exp_f32_e32 v107, v107
	s_waitcnt lgkmcnt(0)
	v_mfma_f32_32x32x16_bf16 v[220:235], v[116:119], v[160:163], v[220:235]
	ds_read_b64_tr_b16 v[4:5], v248 offset:12288
	ds_read_b64_tr_b16 v[6:7], v248 offset:13312
	ds_read_b64_tr_b16 v[8:9], v249 offset:12288
	ds_read_b64_tr_b16 v[10:11], v249 offset:13312
	ds_read_b64_tr_b16 v[12:13], v248 offset:14336
	ds_read_b64_tr_b16 v[14:15], v248 offset:15360
	ds_read_b64_tr_b16 v[116:117], v249 offset:14336
	ds_read_b64_tr_b16 v[118:119], v249 offset:15360
	v_exp_f32_e32 v108, v108
	v_exp_f32_e32 v109, v109
	v_exp_f32_e32 v110, v110
	v_exp_f32_e32 v111, v111
	v_exp_f32_e32 v112, v112
	v_exp_f32_e32 v113, v113
	v_exp_f32_e32 v114, v114
	v_exp_f32_e32 v115, v115
	v_cvt_pk_bf16_f32 v100, v100, v101
	v_cvt_pk_bf16_f32 v101, v102, v103
	v_cvt_pk_bf16_f32 v102, v104, v105
	v_cvt_pk_bf16_f32 v103, v106, v107
	v_cvt_pk_bf16_f32 v104, v108, v109
	v_cvt_pk_bf16_f32 v105, v110, v111
	v_cvt_pk_bf16_f32 v106, v112, v113
	v_cvt_pk_bf16_f32 v107, v114, v115
	ds_read_b64_tr_b16 v[108:109], v249 offset:10240
	ds_read_b64_tr_b16 v[110:111], v249 offset:11264
	v_cndmask_b32_e64 v100, v100, 0, s[22:23]
	v_cndmask_b32_e64 v101, v101, 0, s[22:23]
	v_cndmask_b32_e64 v102, v102, 0, s[22:23]
	v_cndmask_b32_e64 v103, v103, 0, s[22:23]
	v_cndmask_b32_e64 v104, v104, 0, s[22:23]
	v_cndmask_b32_e64 v105, v105, 0, s[22:23]
	v_cndmask_b32_e64 v106, v106, 0, s[22:23]
	v_cndmask_b32_e64 v107, v107, 0, s[22:23]
	v_mfma_f32_32x32x16_bf16 v[36:51], v[236:239], v[100:103], v[36:51]
	v_exp_f32_e32 v220, v220
	v_exp_f32_e32 v221, v221
	v_exp_f32_e32 v222, v222
	v_exp_f32_e32 v223, v223
	v_mfma_f32_32x32x16_bf16 v[20:35], v[240:243], v[100:103], v[20:35]
	v_exp_f32_e32 v224, v224
	v_exp_f32_e32 v225, v225
	v_exp_f32_e32 v226, v226
	v_exp_f32_e32 v227, v227
	v_mfma_f32_32x32x16_bf16 v[52:67], v[252:255], v[100:103], v[52:67]
	v_exp_f32_e32 v228, v228
	v_exp_f32_e32 v229, v229
	v_exp_f32_e32 v230, v230
	v_exp_f32_e32 v231, v231
	v_mfma_f32_32x32x16_bf16 v[36:51], v[244:247], v[104:107], v[36:51]
	v_exp_f32_e32 v232, v232
	v_exp_f32_e32 v233, v233
	v_exp_f32_e32 v234, v234
	v_exp_f32_e32 v235, v235
	s_waitcnt lgkmcnt(0)
	v_mfma_f32_32x32x16_bf16 v[20:35], v[108:111], v[104:107], v[20:35]
	v_cvt_pk_bf16_f32 v220, v220, v221
	v_cvt_pk_bf16_f32 v221, v222, v223
	v_cvt_pk_bf16_f32 v222, v224, v225
	v_cvt_pk_bf16_f32 v223, v226, v227
	v_mfma_f32_32x32x16_bf16 v[52:67], v[252:255], v[104:107], v[52:67]
	v_cvt_pk_bf16_f32 v224, v228, v229
	v_cvt_pk_bf16_f32 v225, v230, v231
	v_cvt_pk_bf16_f32 v226, v232, v233
	v_cvt_pk_bf16_f32 v227, v234, v235
	v_cndmask_b32_e64 v220, v220, 0, s[22:23]
	v_cndmask_b32_e64 v221, v221, 0, s[22:23]
	v_cndmask_b32_e64 v222, v222, 0, s[22:23]
	v_cndmask_b32_e64 v223, v223, 0, s[22:23]
	v_cndmask_b32_e64 v224, v224, 0, s[22:23]
	v_cndmask_b32_e64 v225, v225, 0, s[22:23]
	v_cndmask_b32_e64 v226, v226, 0, s[22:23]
	v_cndmask_b32_e64 v227, v227, 0, s[22:23]
	v_mfma_f32_32x32x16_bf16 v[36:51], v[4:7], v[220:223], v[36:51]
	v_mfma_f32_32x32x16_bf16 v[20:35], v[8:11], v[220:223], v[20:35]
	v_mfma_f32_32x32x16_bf16 v[52:67], v[252:255], v[220:223], v[52:67]
	v_mfma_f32_32x32x16_bf16 v[36:51], v[12:15], v[224:227], v[36:51]
	v_mfma_f32_32x32x16_bf16 v[20:35], v[116:119], v[224:227], v[20:35]
	v_mfma_f32_32x32x16_bf16 v[52:67], v[252:255], v[224:227], v[52:67]
	s_andn2_b64 s[34:35], s[34:35], s[2:3]
	s_add_i32 s78, s78, -1
	s_addk_i32 s79, 0x4000
	s_add_i32 s9, s9, 1
	s_cmp_eq_u32 s78, -1
	s_cbranch_scc0 .LBB0_555
	s_branch .LBB0_582
; #define LAS __attribute__((address_space(3)))
; __device__ __forceinline__ unsigned pk2(float lo, float hi) { f32x2_t v = {lo, hi}; bf16x2_t b = __builtin_convertvector(v, bf16x2_t); return __builtin_bit_cast(unsigned, b); }
; __device__ __forceinline__ float ex2(float x) { return __builtin_amdgcn_exp2f(x); }
; __device__ __forceinline__ void nsa_unit(const Params& p, LAS unsigned char* lds, int b, int hkv, int i, int tid, int lane, int wave) {
;     ...
;                     for (int hf = 0; hf < 2; ++hf) {
;                         f32x16 s; unsigned pw[8];
;                         if (dj <= 2) {
;                             qk_half(stg, qf, col, hi, hf, s, -mref);
;                             const LAS float* l2p = (const LAS float*)(lds + LUT2_OFF) + head * 260 + db + 5;
; #pragma unroll
;                             for (int r = 0; r < 16; ++r) { const float x = s[r] + l2p[63 - KKOF(hf, r)]; s[r] = (lsel && KKOF(hf, r) <= db) ? ex2(x) : 0.f; }
; #pragma unroll
;                             for (int r = 0; r < 8; ++r) pw[r] = pk2(s[2 * r], s[2 * r + 1]);
;                         } else if (dj == 8) {
;                             qk_half_c(stg, qf, col, hi, hf, s, cfar);
; #pragma unroll
;                             for (int r = 0; r < 16; ++r) { const int d_ = db - KKOF(hf, r); s[r] = (lsel && d_ < dmax) ? ex2(s[r]) : 0.f; }
; #pragma unroll
;                             for (int r = 0; r < 8; ++r) pw[r] = pk2(s[2 * r], s[2 * r + 1]);
.Lnotfar:
	s_and_b64 vcc, exec, s[12:13]
	s_cbranch_vccz .LBB0_570
.LBB0_567:
	s_andn2_b64 vcc, exec, s[14:15]
	s_cbranch_vccnz .LBB0_569
	s_waitcnt lgkmcnt(3)
	v_mfma_f32_32x32x16_bf16 v[100:115], v[4:7], v[148:151], v[68:83]
	v_cmp_lt_i32_e32 vcc, s69, v2
	s_or_b64 s[4:5], s[22:23], vcc
	v_cmp_gt_i32_e32 vcc, s8, v2
	v_cmp_gt_i32_e64 s[24:25], s69, v2
	s_waitcnt lgkmcnt(2)
	v_mfma_f32_32x32x16_bf16 v[100:115], v[8:11], v[152:155], v[100:115]
	s_waitcnt lgkmcnt(1)
	v_mfma_f32_32x32x16_bf16 v[100:115], v[12:15], v[156:159], v[100:115]
	s_waitcnt lgkmcnt(0)
	v_mfma_f32_32x32x16_bf16 v[100:115], v[116:119], v[160:163], v[100:115]
	s_nop 11
	v_exp_f32_e32 v16, v100
	v_exp_f32_e32 v100, v102
	v_exp_f32_e32 v17, v101
	v_exp_f32_e32 v101, v103
	v_exp_f32_e32 v102, v104
	v_exp_f32_e32 v103, v105
	v_exp_f32_e32 v104, v106
	v_cndmask_b32_e32 v100, 0, v100, vcc
	v_cmp_gt_i32_e32 vcc, s36, v2
	v_exp_f32_e32 v105, v107
	v_exp_f32_e32 v106, v108
	v_cndmask_b32_e32 v101, 0, v101, vcc
	v_cmp_gt_i32_e32 vcc, s37, v2
	v_cndmask_b32_e64 v107, v100, 0, s[22:23]
	v_exp_f32_e32 v100, v109
	v_cndmask_b32_e32 v102, 0, v102, vcc
	v_cmp_gt_i32_e32 vcc, s38, v2
	v_exp_f32_e32 v108, v110
	v_exp_f32_e32 v110, v112
	v_cndmask_b32_e32 v103, 0, v103, vcc
	v_cmp_gt_i32_e32 vcc, s39, v2
	v_exp_f32_e32 v112, v114
	v_cndmask_b32_e64 v16, 0, v16, s[24:25]
	v_cndmask_b32_e32 v104, 0, v104, vcc
	v_cmp_gt_i32_e32 vcc, s40, v2
	v_cndmask_b32_e64 v17, v17, 0, s[4:5]
	v_cndmask_b32_e64 v16, v16, 0, s[22:23]
	v_cndmask_b32_e32 v105, 0, v105, vcc
	v_cmp_gt_i32_e32 vcc, s41, v2
	v_cndmask_b32_e64 v101, v101, 0, s[22:23]
	v_cndmask_b32_e64 v102, v102, 0, s[22:23]
	v_cndmask_b32_e32 v106, 0, v106, vcc
	v_cmp_gt_i32_e32 vcc, s50, v2
	v_cndmask_b32_e64 v103, v103, 0, s[22:23]
	v_cndmask_b32_e64 v104, v104, 0, s[22:23]
	v_cndmask_b32_e32 v100, 0, v100, vcc
	v_cndmask_b32_e64 v109, v100, 0, s[22:23]
	v_exp_f32_e32 v100, v111
	v_cmp_gt_i32_e32 vcc, s51, v2
	v_cndmask_b32_e64 v105, v105, 0, s[22:23]
	v_cndmask_b32_e64 v106, v106, 0, s[22:23]
	v_cndmask_b32_e32 v108, 0, v108, vcc
	v_cmp_gt_i32_e32 vcc, s52, v2
	v_cndmask_b32_e64 v108, v108, 0, s[22:23]
	v_cvt_pk_bf16_f32 v101, v107, v101
	v_cndmask_b32_e32 v100, 0, v100, vcc
	v_cndmask_b32_e64 v111, v100, 0, s[22:23]
	v_exp_f32_e32 v100, v113
	v_cmp_gt_i32_e32 vcc, s53, v2
	v_cvt_pk_bf16_f32 v102, v102, v103
	v_cvt_pk_bf16_f32 v103, v104, v105
	v_cndmask_b32_e32 v110, 0, v110, vcc
	v_cmp_gt_i32_e32 vcc, s54, v2
	v_cndmask_b32_e64 v110, v110, 0, s[22:23]
	v_cvt_pk_bf16_f32 v104, v106, v109
	v_cndmask_b32_e32 v100, 0, v100, vcc
	v_cndmask_b32_e64 v113, v100, 0, s[22:23]
	v_exp_f32_e32 v100, v115
	v_cmp_gt_i32_e32 vcc, s55, v2
	v_cvt_pk_bf16_f32 v105, v108, v111
	v_cvt_pk_bf16_f32 v106, v110, v113
	v_cndmask_b32_e32 v112, 0, v112, vcc
	v_cmp_gt_i32_e32 vcc, s56, v2
	v_cndmask_b32_e64 v112, v112, 0, s[22:23]
	s_nop 0
	v_cndmask_b32_e32 v100, 0, v100, vcc
	v_cndmask_b32_e64 v114, v100, 0, s[22:23]
	v_cvt_pk_bf16_f32 v100, v16, v17
	v_cvt_pk_bf16_f32 v107, v112, v114
